# row phases k=2,k=6: nt (streaming) cache policy on the XB/H stores
# speedup vs baseline: 1.0031x; 1.0020x over previous
.LBB0_56:
	s_add_i32 s4, s2, 1
	s_cmp_lt_i32 s4, s6
	s_cselect_b64 s[4:5], -1, 0
	v_cndmask_b32_e64 v64, 0, 1, s[4:5]
	v_mov_b32_e32 v65, s59
	v_add_co_u32_e32 v128, vcc, 0x2000000, v94
	v_lshl_add_u64 v[64:65], v[64:65], 0, s[2:3]
	s_nop 0
	v_addc_co_u32_e32 v129, vcc, 0, v95, vcc
	v_lshl_add_u64 v[64:65], v[64:65], 0, v[72:73]
	global_load_dwordx4 v[100:103], v[128:129], off
	global_load_dwordx4 v[104:107], v[128:129], off offset:1024
	global_load_dwordx4 v[116:119], v[94:95], off
	global_load_dwordx4 v[120:123], v[94:95], off offset:1024
	v_lshlrev_b64 v[64:65], 11, v[64:65]
	v_lshl_add_u64 v[98:99], v[90:91], 0, v[64:65]
	v_lshl_add_u64 v[96:97], v[92:93], 0, v[64:65]
	global_load_dwordx4 v[108:111], v[98:99], off
	global_load_dwordx4 v[124:127], v[98:99], off offset:1024
	global_load_dwordx4 v[68:71], v[96:97], off
	global_load_dwordx4 v[64:67], v[96:97], off offset:1024
	s_waitcnt vmcnt(7)
	v_lshlrev_b32_e32 v130, 16, v100
	v_and_b32_e32 v131, 0xffff0000, v100
	v_lshlrev_b32_e32 v150, 16, v101
	v_and_b32_e32 v151, 0xffff0000, v101
	v_lshlrev_b32_e32 v152, 16, v102
	v_and_b32_e32 v153, 0xffff0000, v102
	v_lshlrev_b32_e32 v154, 16, v103
	v_and_b32_e32 v155, 0xffff0000, v103
	s_waitcnt vmcnt(2)
	v_lshlrev_b32_e32 v100, 16, v126
	v_and_b32_e32 v101, 0xffff0000, v126
	v_lshlrev_b32_e32 v102, 16, v127
	v_and_b32_e32 v103, 0xffff0000, v127
	v_and_b32_e32 v127, 0xffff0000, v118
	v_and_b32_e32 v126, 0xffff0000, v116
	v_lshlrev_b32_e32 v156, 16, v104
	v_and_b32_e32 v157, 0xffff0000, v104
	v_lshlrev_b32_e32 v158, 16, v105
	v_and_b32_e32 v159, 0xffff0000, v105
	v_lshlrev_b32_e32 v160, 16, v106
	v_and_b32_e32 v161, 0xffff0000, v106
	v_lshlrev_b32_e32 v162, 16, v107
	v_and_b32_e32 v163, 0xffff0000, v107
	v_lshlrev_b32_e32 v104, 16, v124
	v_and_b32_e32 v105, 0xffff0000, v124
	v_lshlrev_b32_e32 v106, 16, v125
	v_and_b32_e32 v107, 0xffff0000, v125
	v_lshlrev_b32_e32 v125, 16, v118
	v_lshlrev_b32_e32 v124, 16, v116
	v_lshlrev_b32_e32 v164, 16, v117
	v_and_b32_e32 v118, 0xffff0000, v117
	v_pk_mul_f32 v[116:117], v[126:127], v[126:127]
	v_and_b32_e32 v169, 0xffff0000, v120
	v_and_b32_e32 v168, 0xffff0000, v122
	v_lshlrev_b32_e32 v165, 16, v119
	v_pk_fma_f32 v[116:117], v[124:125], v[124:125], v[116:117]
	v_lshlrev_b32_e32 v167, 16, v120
	v_lshlrev_b32_e32 v166, 16, v122
	v_lshlrev_b32_e32 v170, 16, v123
	v_and_b32_e32 v120, 0xffff0000, v123
	v_pk_mul_f32 v[122:123], v[168:169], v[168:169]
	v_and_b32_e32 v119, 0xffff0000, v119
	v_pk_fma_f32 v[116:117], v[164:165], v[164:165], v[116:117]
	v_lshlrev_b32_e32 v171, 16, v121
	v_pk_fma_f32 v[122:123], v[166:167], v[166:167], v[122:123]
	v_pk_fma_f32 v[116:117], v[118:119], v[118:119], v[116:117]
	v_and_b32_e32 v121, 0xffff0000, v121
	v_pk_fma_f32 v[122:123], v[170:171], v[170:171], v[122:123]
	v_add_f32_e32 v116, v116, v117
	v_pk_fma_f32 v[122:123], v[120:121], v[120:121], v[122:123]
	v_mov_b32_e32 v173, v126
	v_add_f32_e32 v116, v116, v123
	v_add_f32_e32 v116, v122, v116
	v_mov_b32_e32 v123, v118
	v_mov_b32_e32 v118, v165
	v_add_f32_dpp v116, v116, v116 quad_perm:[1,0,3,2] row_mask:0xf bank_mask:0xf bound_ctrl:1
	v_mov_b32_e32 v126, v125
	v_mov_b32_e32 v122, v164
	v_add_f32_dpp v116, v116, v116 quad_perm:[2,3,0,1] row_mask:0xf bank_mask:0xf bound_ctrl:1
	v_mov_b32_e32 v172, v124
	v_lshlrev_b32_e32 v114, 16, v109
	v_add_f32_dpp v116, v116, v116 row_half_mirror row_mask:0xf bank_mask:0xf bound_ctrl:1
	v_and_b32_e32 v115, 0xffff0000, v109
	v_lshlrev_b32_e32 v112, 16, v108
	v_add_f32_dpp v116, v116, v116 row_mirror row_mask:0xf bank_mask:0xf bound_ctrl:1
	v_and_b32_e32 v113, 0xffff0000, v108
	v_readlane_b32 s7, v116, 16
	v_readlane_b32 s8, v116, 48
	v_readlane_b32 s4, v116, 0
	v_readlane_b32 s5, v116, 32
	v_mov_b32_e32 v116, s7
	v_mov_b32_e32 v117, s8
	v_pk_add_f32 v[116:117], s[4:5], v[116:117]
	v_lshlrev_b32_e32 v108, 16, v110
	v_add_f32_e32 v116, v116, v117
	v_fmamk_f32 v116, v116, 0x3a800000, v137
	v_cmp_gt_f32_e32 vcc, s94, v116
	v_mul_f32_e32 v117, 0x4b800000, v116
	v_and_b32_e32 v109, 0xffff0000, v110
	v_cndmask_b32_e32 v116, v116, v117, vcc
	v_rsq_f32_e32 v116, v116
	v_lshlrev_b32_e32 v110, 16, v111
	v_and_b32_e32 v111, 0xffff0000, v111
	s_add_u32 s2, s2, 2
	v_mul_f32_e32 v117, 0x45800000, v116
	v_cndmask_b32_e32 v116, v116, v117, vcc
	v_pk_mul_f32 v[118:119], v[116:117], v[118:119] op_sel_hi:[0,1]
	v_pk_mul_f32 v[118:119], v[10:11], v[118:119]
	v_pk_mul_f32 v[124:125], v[116:117], v[126:127] op_sel_hi:[0,1]
	v_pk_fma_f32 v[126:127], v[2:3], v[118:119], v[154:155]
	v_mov_b32_e32 v118, v171
	v_mov_b32_e32 v119, v121
	v_pk_mul_f32 v[122:123], v[116:117], v[122:123] op_sel_hi:[0,1]
	v_pk_mul_f32 v[118:119], v[116:117], v[118:119] op_sel_hi:[0,1]
	v_pk_mul_f32 v[122:123], v[14:15], v[122:123]
	v_pk_mul_f32 v[124:125], v[8:9], v[124:125]
	v_pk_mul_f32 v[118:119], v[30:31], v[118:119]
	v_mov_b32_e32 v171, v120
	v_pk_fma_f32 v[122:123], v[6:7], v[122:123], v[150:151]
	v_pk_fma_f32 v[124:125], v[0:1], v[124:125], v[152:153]
	v_mov_b32_e32 v150, v167
	v_mov_b32_e32 v151, v169
	v_pk_fma_f32 v[152:153], v[22:23], v[118:119], v[158:159]
	v_pk_mul_f32 v[118:119], v[116:117], v[170:171] op_sel_hi:[0,1]
	v_mov_b32_e32 v167, v168
	v_pk_mul_f32 v[172:173], v[116:117], v[172:173] op_sel_hi:[0,1]
	v_pk_mul_f32 v[150:151], v[116:117], v[150:151] op_sel_hi:[0,1]
	v_pk_mul_f32 v[116:117], v[116:117], v[166:167] op_sel_hi:[0,1]
	v_pk_mul_f32 v[118:119], v[26:27], v[118:119]
	v_pk_mul_f32 v[172:173], v[12:13], v[172:173]
	v_pk_mul_f32 v[116:117], v[24:25], v[116:117]
	v_pk_fma_f32 v[120:121], v[18:19], v[118:119], v[162:163]
	v_cvt_pk_bf16_f32 v118, v124, v125
	v_cvt_pk_bf16_f32 v119, v126, v127
	v_pk_fma_f32 v[130:131], v[4:5], v[172:173], v[130:131]
	v_pk_mul_f32 v[150:151], v[28:29], v[150:151]
	v_pk_fma_f32 v[154:155], v[16:17], v[116:117], v[160:161]
	v_cvt_pk_bf16_f32 v116, v130, v131
	v_cvt_pk_bf16_f32 v117, v122, v123
	global_store_dwordx4 v[128:129], v[116:119], off nt
	v_pk_fma_f32 v[150:151], v[20:21], v[150:151], v[156:157]
	s_addc_u32 s3, s3, 0
	v_cvt_pk_bf16_f32 v118, v154, v155
	v_cvt_pk_bf16_f32 v119, v120, v121
	v_cvt_pk_bf16_f32 v116, v150, v151
	v_cvt_pk_bf16_f32 v117, v152, v153
	global_store_dwordx4 v[128:129], v[116:119], off offset:1024 nt
	v_mov_b32_e32 v128, v155
	v_mov_b32_e32 v129, v151
	v_mov_b32_e32 v118, v131
	v_mov_b32_e32 v119, v125
	v_mov_b32_e32 v116, v130
	v_mov_b32_e32 v117, v124
	v_pk_mul_f32 v[118:119], v[118:119], v[118:119]
	v_pk_mul_f32 v[128:129], v[128:129], v[128:129]
	v_pk_fma_f32 v[116:117], v[116:117], v[116:117], v[118:119]
	v_mov_b32_e32 v118, v122
	v_mov_b32_e32 v119, v126
	v_pk_fma_f32 v[116:117], v[118:119], v[118:119], v[116:117]
	v_mov_b32_e32 v118, v123
	v_mov_b32_e32 v119, v127
	v_pk_fma_f32 v[116:117], v[118:119], v[118:119], v[116:117]
	v_mov_b32_e32 v118, v154
	v_mov_b32_e32 v119, v150
	v_pk_fma_f32 v[118:119], v[118:119], v[118:119], v[128:129]
	v_mov_b32_e32 v128, v120
	v_mov_b32_e32 v129, v152
	v_pk_fma_f32 v[118:119], v[128:129], v[128:129], v[118:119]
	v_mov_b32_e32 v128, v121
	v_mov_b32_e32 v129, v153
	v_pk_fma_f32 v[118:119], v[128:129], v[128:129], v[118:119]
	v_add_f32_e32 v116, v116, v117
	v_add_f32_e32 v116, v119, v116
	v_add_f32_e32 v116, v118, v116
	s_cmp_ge_i32 s2, s6
	s_nop 0
	v_add_f32_dpp v116, v116, v116 quad_perm:[1,0,3,2] row_mask:0xf bank_mask:0xf bound_ctrl:1
	s_nop 1
	v_add_f32_dpp v116, v116, v116 quad_perm:[2,3,0,1] row_mask:0xf bank_mask:0xf bound_ctrl:1
	s_nop 1
	v_add_f32_dpp v116, v116, v116 row_half_mirror row_mask:0xf bank_mask:0xf bound_ctrl:1
	s_nop 1
	v_add_f32_dpp v116, v116, v116 row_mirror row_mask:0xf bank_mask:0xf bound_ctrl:1
	s_nop 0
	v_readlane_b32 s7, v116, 16
	v_readlane_b32 s8, v116, 48
	v_readlane_b32 s4, v116, 0
	v_readlane_b32 s5, v116, 32
	v_mov_b32_e32 v116, s7
	v_mov_b32_e32 v117, s8
	v_pk_add_f32 v[116:117], s[4:5], v[116:117]
	s_nop 0
	v_add_f32_e32 v116, v116, v117
	v_fmamk_f32 v116, v116, 0x3a800000, v137
	v_cmp_gt_f32_e32 vcc, s94, v116
	v_mul_f32_e32 v117, 0x4b800000, v116
	s_nop 0
	v_cndmask_b32_e32 v116, v116, v117, vcc
	v_rsq_f32_e32 v116, v116
	s_nop 0
	v_mul_f32_e32 v117, 0x45800000, v116
	v_cndmask_b32_e32 v116, v116, v117, vcc
	v_pk_mul_f32 v[118:119], v[122:123], v[116:117] op_sel_hi:[1,0]
	v_pk_mul_f32 v[122:123], v[130:131], v[116:117] op_sel_hi:[1,0]
	v_pk_mul_f32 v[118:119], v[46:47], v[118:119]
	v_pk_mul_f32 v[126:127], v[126:127], v[116:117] op_sel_hi:[1,0]
	v_pk_mul_f32 v[124:125], v[124:125], v[116:117] op_sel_hi:[1,0]
	v_pk_mul_f32 v[128:129], v[152:153], v[116:117] op_sel_hi:[1,0]
	v_pk_mul_f32 v[130:131], v[150:151], v[116:117] op_sel_hi:[1,0]
	v_pk_mul_f32 v[120:121], v[120:121], v[116:117] op_sel_hi:[1,0]
	v_pk_mul_f32 v[116:117], v[154:155], v[116:117] op_sel_hi:[1,0]
	v_pk_fma_f32 v[118:119], v[74:75], v[118:119], v[38:39]
	v_pk_mul_f32 v[124:125], v[40:41], v[124:125]
	v_pk_mul_f32 v[126:127], v[42:43], v[126:127]
	v_pk_mul_f32 v[116:117], v[56:57], v[116:117]
	v_pk_mul_f32 v[122:123], v[44:45], v[122:123]
	v_pk_fma_f32 v[126:127], v[78:79], v[126:127], v[34:35]
	v_pk_fma_f32 v[124:125], v[80:81], v[124:125], v[32:33]
	v_pk_mul_f32 v[120:121], v[58:59], v[120:121]
	v_pk_fma_f32 v[150:151], v[88:89], v[116:117], v[48:49]
	v_cvt_pk_bf16_f32 v117, v118, v119
	v_cvt_pk_bf16_f32 v118, v124, v125
	v_cvt_pk_bf16_f32 v119, v126, v127
	v_pk_fma_f32 v[122:123], v[76:77], v[122:123], v[36:37]
	v_pk_mul_f32 v[130:131], v[60:61], v[130:131]
	v_pk_mul_f32 v[128:129], v[62:63], v[128:129]
	v_pk_fma_f32 v[120:121], v[86:87], v[120:121], v[50:51]
	v_cvt_pk_bf16_f32 v116, v122, v123
	global_store_dwordx4 v[94:95], v[116:119], off nt
	v_pk_fma_f32 v[128:129], v[82:83], v[128:129], v[54:55]
	v_pk_fma_f32 v[130:131], v[84:85], v[130:131], v[52:53]
	v_cvt_pk_bf16_f32 v118, v150, v151
	v_cvt_pk_bf16_f32 v119, v120, v121
	v_cvt_pk_bf16_f32 v117, v128, v129
	s_waitcnt vmcnt(4)
	v_lshlrev_b32_e32 v120, 16, v69
	v_cvt_pk_bf16_f32 v116, v130, v131
	global_store_dwordx4 v[94:95], v[116:119], off offset:1024 nt
	s_waitcnt vmcnt(4)
	v_and_b32_e32 v125, 0xffff0000, v64
	v_and_b32_e32 v124, 0xffff0000, v66
	v_and_b32_e32 v119, 0xffff0000, v70
	v_and_b32_e32 v118, 0xffff0000, v68
	v_lshlrev_b32_e32 v117, 16, v70
	v_lshlrev_b32_e32 v116, 16, v68
	v_and_b32_e32 v70, 0xffff0000, v69
	v_pk_mul_f32 v[68:69], v[118:119], v[118:119]
	v_lshlrev_b32_e32 v121, 16, v71
	v_pk_fma_f32 v[68:69], v[116:117], v[116:117], v[68:69]
	v_lshlrev_b32_e32 v123, 16, v64
	v_lshlrev_b32_e32 v122, 16, v66
	v_lshlrev_b32_e32 v126, 16, v67
	v_and_b32_e32 v64, 0xffff0000, v67
	v_pk_mul_f32 v[66:67], v[124:125], v[124:125]
	v_and_b32_e32 v71, 0xffff0000, v71
	v_pk_fma_f32 v[68:69], v[120:121], v[120:121], v[68:69]
	v_lshlrev_b32_e32 v127, 16, v65
	v_pk_fma_f32 v[66:67], v[122:123], v[122:123], v[66:67]
	v_pk_fma_f32 v[68:69], v[70:71], v[70:71], v[68:69]
	v_and_b32_e32 v65, 0xffff0000, v65
	v_pk_fma_f32 v[66:67], v[126:127], v[126:127], v[66:67]
	v_add_f32_e32 v68, v68, v69
	v_pk_fma_f32 v[66:67], v[64:65], v[64:65], v[66:67]
	v_mov_b32_e32 v69, v70
	v_add_f32_e32 v67, v68, v67
	v_add_f32_e32 v66, v66, v67
	v_mov_b32_e32 v68, v120
	v_mov_b32_e32 v129, v118
	v_add_f32_dpp v66, v66, v66 quad_perm:[1,0,3,2] row_mask:0xf bank_mask:0xf bound_ctrl:1
	v_mov_b32_e32 v70, v121
	v_mov_b32_e32 v118, v117
	v_add_f32_dpp v66, v66, v66 quad_perm:[2,3,0,1] row_mask:0xf bank_mask:0xf bound_ctrl:1
	v_mov_b32_e32 v128, v116
	v_lshl_add_u64 v[94:95], v[94:95], 0, s[30:31]
	v_add_f32_dpp v66, v66, v66 row_half_mirror row_mask:0xf bank_mask:0xf bound_ctrl:1
	s_nop 1
	v_add_f32_dpp v66, v66, v66 row_mirror row_mask:0xf bank_mask:0xf bound_ctrl:1
	s_nop 0
	v_readlane_b32 s7, v66, 16
	v_readlane_b32 s8, v66, 48
	v_readlane_b32 s4, v66, 0
	v_readlane_b32 s5, v66, 32
	v_mov_b32_e32 v66, s7
	v_mov_b32_e32 v67, s8
	v_pk_add_f32 v[66:67], s[4:5], v[66:67]
	s_nop 0
	v_add_f32_e32 v66, v66, v67
	v_fmamk_f32 v66, v66, 0x3a800000, v137
	v_cmp_gt_f32_e32 vcc, s94, v66
	v_mul_f32_e32 v67, 0x4b800000, v66
	s_nop 0
	v_cndmask_b32_e32 v66, v66, v67, vcc
	v_rsq_f32_e32 v66, v66
	s_nop 0
	v_mul_f32_e32 v67, 0x45800000, v66
	v_cndmask_b32_e32 v66, v66, v67, vcc
	v_pk_mul_f32 v[68:69], v[66:67], v[68:69] op_sel_hi:[0,1]
	v_pk_mul_f32 v[68:69], v[14:15], v[68:69]
	v_pk_mul_f32 v[70:71], v[66:67], v[70:71] op_sel_hi:[0,1]
	v_pk_fma_f32 v[68:69], v[6:7], v[68:69], v[114:115]
	v_pk_mul_f32 v[114:115], v[66:67], v[118:119] op_sel_hi:[0,1]
	v_pk_mul_f32 v[114:115], v[8:9], v[114:115]
	v_pk_mul_f32 v[70:71], v[10:11], v[70:71]
	v_pk_fma_f32 v[108:109], v[0:1], v[114:115], v[108:109]
	v_pk_fma_f32 v[70:71], v[2:3], v[70:71], v[110:111]
	v_mov_b32_e32 v110, v127
	v_mov_b32_e32 v111, v65
	v_mov_b32_e32 v114, v123
	v_mov_b32_e32 v115, v125
	v_mov_b32_e32 v127, v64
	v_mov_b32_e32 v123, v124
	v_pk_mul_f32 v[128:129], v[66:67], v[128:129] op_sel_hi:[0,1]
	v_pk_mul_f32 v[110:111], v[66:67], v[110:111] op_sel_hi:[0,1]
	v_pk_mul_f32 v[114:115], v[66:67], v[114:115] op_sel_hi:[0,1]
	v_pk_mul_f32 v[64:65], v[66:67], v[126:127] op_sel_hi:[0,1]
	v_pk_mul_f32 v[66:67], v[66:67], v[122:123] op_sel_hi:[0,1]
	v_pk_mul_f32 v[66:67], v[24:25], v[66:67]
	v_pk_mul_f32 v[128:129], v[12:13], v[128:129]
	v_pk_mul_f32 v[64:65], v[26:27], v[64:65]
	v_pk_fma_f32 v[100:101], v[16:17], v[66:67], v[100:101]
	v_cvt_pk_bf16_f32 v66, v108, v109
	v_cvt_pk_bf16_f32 v67, v70, v71
	v_pk_fma_f32 v[112:113], v[4:5], v[128:129], v[112:113]
	v_pk_mul_f32 v[114:115], v[28:29], v[114:115]
	v_pk_mul_f32 v[110:111], v[30:31], v[110:111]
	v_pk_fma_f32 v[102:103], v[18:19], v[64:65], v[102:103]
	v_cvt_pk_bf16_f32 v64, v112, v113
	v_cvt_pk_bf16_f32 v65, v68, v69
	global_store_dwordx4 v[98:99], v[64:67], off nt
	v_pk_fma_f32 v[106:107], v[22:23], v[110:111], v[106:107]
	v_pk_fma_f32 v[104:105], v[20:21], v[114:115], v[104:105]
	v_cvt_pk_bf16_f32 v66, v100, v101
	v_cvt_pk_bf16_f32 v67, v102, v103
	v_cvt_pk_bf16_f32 v65, v106, v107
	s_nop 0
	v_cvt_pk_bf16_f32 v64, v104, v105
	global_store_dwordx4 v[98:99], v[64:67], off offset:1024 nt
	v_mov_b32_e32 v98, v101
	v_mov_b32_e32 v99, v105
	v_mov_b32_e32 v66, v113
	v_mov_b32_e32 v67, v109
	v_mov_b32_e32 v64, v112
	v_mov_b32_e32 v65, v108
	v_pk_mul_f32 v[66:67], v[66:67], v[66:67]
	v_pk_mul_f32 v[98:99], v[98:99], v[98:99]
	v_pk_fma_f32 v[64:65], v[64:65], v[64:65], v[66:67]
	v_mov_b32_e32 v66, v68
	v_mov_b32_e32 v67, v70
	v_pk_fma_f32 v[64:65], v[66:67], v[66:67], v[64:65]
	v_mov_b32_e32 v66, v69
	v_mov_b32_e32 v67, v71
	v_pk_fma_f32 v[64:65], v[66:67], v[66:67], v[64:65]
	v_mov_b32_e32 v66, v100
	v_mov_b32_e32 v67, v104
	v_pk_fma_f32 v[66:67], v[66:67], v[66:67], v[98:99]
	v_mov_b32_e32 v98, v102
	v_mov_b32_e32 v99, v106
	v_pk_fma_f32 v[66:67], v[98:99], v[98:99], v[66:67]
	v_mov_b32_e32 v98, v103
	v_mov_b32_e32 v99, v107
	v_pk_fma_f32 v[66:67], v[98:99], v[98:99], v[66:67]
	v_add_f32_e32 v64, v64, v65
	v_add_f32_e32 v64, v67, v64
	v_add_f32_e32 v64, v66, v64
	s_nop 1
	v_add_f32_dpp v64, v64, v64 quad_perm:[1,0,3,2] row_mask:0xf bank_mask:0xf bound_ctrl:1
	s_nop 1
	v_add_f32_dpp v64, v64, v64 quad_perm:[2,3,0,1] row_mask:0xf bank_mask:0xf bound_ctrl:1
	s_nop 1
	v_add_f32_dpp v64, v64, v64 row_half_mirror row_mask:0xf bank_mask:0xf bound_ctrl:1
	s_nop 1
	v_add_f32_dpp v64, v64, v64 row_mirror row_mask:0xf bank_mask:0xf bound_ctrl:1
	s_nop 0
	v_readlane_b32 s7, v64, 16
	v_readlane_b32 s8, v64, 48
	v_readlane_b32 s4, v64, 0
	v_readlane_b32 s5, v64, 32
	v_mov_b32_e32 v64, s7
	v_mov_b32_e32 v65, s8
	v_pk_add_f32 v[64:65], s[4:5], v[64:65]
	s_nop 0
	v_add_f32_e32 v64, v64, v65
	v_fmamk_f32 v64, v64, 0x3a800000, v137
	v_cmp_gt_f32_e32 vcc, s94, v64
	v_mul_f32_e32 v65, 0x4b800000, v64
	s_nop 0
	v_cndmask_b32_e32 v64, v64, v65, vcc
	v_rsq_f32_e32 v64, v64
	s_nop 0
	v_mul_f32_e32 v65, 0x45800000, v64
	v_cndmask_b32_e32 v64, v64, v65, vcc
	v_pk_mul_f32 v[66:67], v[68:69], v[64:65] op_sel_hi:[1,0]
	v_pk_mul_f32 v[68:69], v[112:113], v[64:65] op_sel_hi:[1,0]
	v_pk_mul_f32 v[66:67], v[46:47], v[66:67]
	v_pk_mul_f32 v[70:71], v[70:71], v[64:65] op_sel_hi:[1,0]
	v_pk_mul_f32 v[98:99], v[108:109], v[64:65] op_sel_hi:[1,0]
	v_pk_mul_f32 v[106:107], v[106:107], v[64:65] op_sel_hi:[1,0]
	v_pk_mul_f32 v[104:105], v[104:105], v[64:65] op_sel_hi:[1,0]
	v_pk_mul_f32 v[102:103], v[102:103], v[64:65] op_sel_hi:[1,0]
	v_pk_mul_f32 v[64:65], v[100:101], v[64:65] op_sel_hi:[1,0]
	v_pk_mul_f32 v[68:69], v[44:45], v[68:69]
	v_pk_fma_f32 v[66:67], v[74:75], v[66:67], v[38:39]
	v_pk_mul_f32 v[98:99], v[40:41], v[98:99]
	v_pk_mul_f32 v[70:71], v[42:43], v[70:71]
	v_pk_mul_f32 v[64:65], v[56:57], v[64:65]
	v_pk_fma_f32 v[68:69], v[76:77], v[68:69], v[36:37]
	v_pk_fma_f32 v[70:71], v[78:79], v[70:71], v[34:35]
	v_pk_fma_f32 v[98:99], v[80:81], v[98:99], v[32:33]
	v_pk_mul_f32 v[104:105], v[60:61], v[104:105]
	v_pk_mul_f32 v[106:107], v[62:63], v[106:107]
	v_pk_mul_f32 v[100:101], v[58:59], v[102:103]
	v_pk_fma_f32 v[102:103], v[88:89], v[64:65], v[48:49]
	v_cvt_pk_bf16_f32 v64, v68, v69
	v_cvt_pk_bf16_f32 v65, v66, v67
	v_cvt_pk_bf16_f32 v66, v98, v99
	v_cvt_pk_bf16_f32 v67, v70, v71
	v_pk_fma_f32 v[106:107], v[82:83], v[106:107], v[54:55]
	v_pk_fma_f32 v[104:105], v[84:85], v[104:105], v[52:53]
	v_pk_fma_f32 v[100:101], v[86:87], v[100:101], v[50:51]
	global_store_dwordx4 v[96:97], v[64:67], off nt
	s_nop 1
	v_cvt_pk_bf16_f32 v64, v104, v105
	v_cvt_pk_bf16_f32 v65, v106, v107
	v_cvt_pk_bf16_f32 v66, v102, v103
	v_cvt_pk_bf16_f32 v67, v100, v101
	global_store_dwordx4 v[96:97], v[64:67], off offset:1024 nt
	s_cbranch_scc0 .LBB0_56

.LBB0_1086:
	s_add_i32 s4, s2, 1
	s_cmp_lt_i32 s4, s8
	s_cselect_b64 s[4:5], -1, 0
	v_cndmask_b32_e64 v48, 0, 1, s[4:5]
	v_mov_b32_e32 v49, s59
	v_add_co_u32_e32 v128, vcc, 0x2000000, v94
	v_lshl_add_u64 v[48:49], v[48:49], 0, s[2:3]
	s_nop 0
	v_addc_co_u32_e32 v129, vcc, 0, v95, vcc
	v_lshl_add_u64 v[48:49], v[48:49], 0, v[56:57]
	global_load_dwordx4 v[100:103], v[128:129], off
	global_load_dwordx4 v[104:107], v[128:129], off offset:1024
	global_load_dwordx4 v[116:119], v[94:95], off
	global_load_dwordx4 v[120:123], v[94:95], off offset:1024
	v_lshlrev_b64 v[48:49], 11, v[48:49]
	v_lshl_add_u64 v[98:99], v[90:91], 0, v[48:49]
	v_lshl_add_u64 v[96:97], v[92:93], 0, v[48:49]
	global_load_dwordx4 v[108:111], v[98:99], off
	global_load_dwordx4 v[124:127], v[98:99], off offset:1024
	global_load_dwordx4 v[52:55], v[96:97], off
	global_load_dwordx4 v[48:51], v[96:97], off offset:1024
	s_waitcnt vmcnt(7)
	v_lshlrev_b32_e32 v130, 16, v100
	v_and_b32_e32 v131, 0xffff0000, v100
	v_lshlrev_b32_e32 v150, 16, v101
	v_and_b32_e32 v151, 0xffff0000, v101
	v_lshlrev_b32_e32 v152, 16, v102
	v_and_b32_e32 v153, 0xffff0000, v102
	v_lshlrev_b32_e32 v154, 16, v103
	v_and_b32_e32 v155, 0xffff0000, v103
	s_waitcnt vmcnt(2)
	v_lshlrev_b32_e32 v100, 16, v126
	v_and_b32_e32 v101, 0xffff0000, v126
	v_lshlrev_b32_e32 v102, 16, v127
	v_and_b32_e32 v103, 0xffff0000, v127
	v_and_b32_e32 v127, 0xffff0000, v118
	v_and_b32_e32 v126, 0xffff0000, v116
	v_lshlrev_b32_e32 v156, 16, v104
	v_and_b32_e32 v157, 0xffff0000, v104
	v_lshlrev_b32_e32 v158, 16, v105
	v_and_b32_e32 v159, 0xffff0000, v105
	v_lshlrev_b32_e32 v160, 16, v106
	v_and_b32_e32 v161, 0xffff0000, v106
	v_lshlrev_b32_e32 v162, 16, v107
	v_and_b32_e32 v163, 0xffff0000, v107
	v_lshlrev_b32_e32 v104, 16, v124
	v_and_b32_e32 v105, 0xffff0000, v124
	v_lshlrev_b32_e32 v106, 16, v125
	v_and_b32_e32 v107, 0xffff0000, v125
	v_lshlrev_b32_e32 v125, 16, v118
	v_lshlrev_b32_e32 v124, 16, v116
	v_lshlrev_b32_e32 v164, 16, v117
	v_and_b32_e32 v118, 0xffff0000, v117
	v_pk_mul_f32 v[116:117], v[126:127], v[126:127]
	v_and_b32_e32 v169, 0xffff0000, v120
	v_and_b32_e32 v168, 0xffff0000, v122
	v_lshlrev_b32_e32 v165, 16, v119
	v_pk_fma_f32 v[116:117], v[124:125], v[124:125], v[116:117]
	v_lshlrev_b32_e32 v167, 16, v120
	v_lshlrev_b32_e32 v166, 16, v122
	v_lshlrev_b32_e32 v170, 16, v123
	v_and_b32_e32 v120, 0xffff0000, v123
	v_pk_mul_f32 v[122:123], v[168:169], v[168:169]
	v_and_b32_e32 v119, 0xffff0000, v119
	v_pk_fma_f32 v[116:117], v[164:165], v[164:165], v[116:117]
	v_lshlrev_b32_e32 v171, 16, v121
	v_pk_fma_f32 v[122:123], v[166:167], v[166:167], v[122:123]
	v_pk_fma_f32 v[116:117], v[118:119], v[118:119], v[116:117]
	v_and_b32_e32 v121, 0xffff0000, v121
	v_pk_fma_f32 v[122:123], v[170:171], v[170:171], v[122:123]
	v_add_f32_e32 v116, v116, v117
	v_pk_fma_f32 v[122:123], v[120:121], v[120:121], v[122:123]
	v_mov_b32_e32 v173, v126
	v_add_f32_e32 v116, v116, v123
	v_add_f32_e32 v116, v122, v116
	v_mov_b32_e32 v123, v118
	v_mov_b32_e32 v118, v165
	v_add_f32_dpp v116, v116, v116 quad_perm:[1,0,3,2] row_mask:0xf bank_mask:0xf bound_ctrl:1
	v_mov_b32_e32 v126, v125
	v_mov_b32_e32 v122, v164
	v_add_f32_dpp v116, v116, v116 quad_perm:[2,3,0,1] row_mask:0xf bank_mask:0xf bound_ctrl:1
	v_mov_b32_e32 v172, v124
	v_lshlrev_b32_e32 v114, 16, v109
	v_add_f32_dpp v116, v116, v116 row_half_mirror row_mask:0xf bank_mask:0xf bound_ctrl:1
	v_and_b32_e32 v115, 0xffff0000, v109
	v_lshlrev_b32_e32 v112, 16, v108
	v_add_f32_dpp v116, v116, v116 row_mirror row_mask:0xf bank_mask:0xf bound_ctrl:1
	v_and_b32_e32 v113, 0xffff0000, v108
	v_readlane_b32 s6, v116, 16
	v_readlane_b32 s7, v116, 48
	v_readlane_b32 s4, v116, 0
	v_readlane_b32 s5, v116, 32
	v_mov_b32_e32 v116, s6
	v_mov_b32_e32 v117, s7
	v_pk_add_f32 v[116:117], s[4:5], v[116:117]
	v_lshlrev_b32_e32 v108, 16, v110
	v_add_f32_e32 v116, v116, v117
	v_fmamk_f32 v116, v116, 0x3a800000, v137
	v_cmp_gt_f32_e32 vcc, s94, v116
	v_mul_f32_e32 v117, 0x4b800000, v116
	v_and_b32_e32 v109, 0xffff0000, v110
	v_cndmask_b32_e32 v116, v116, v117, vcc
	v_rsq_f32_e32 v116, v116
	v_lshlrev_b32_e32 v110, 16, v111
	v_and_b32_e32 v111, 0xffff0000, v111
	s_add_u32 s2, s2, 2
	v_mul_f32_e32 v117, 0x45800000, v116
	v_cndmask_b32_e32 v116, v116, v117, vcc
	v_pk_mul_f32 v[118:119], v[116:117], v[118:119] op_sel_hi:[0,1]
	v_pk_mul_f32 v[118:119], v[2:3], v[118:119]
	v_pk_mul_f32 v[124:125], v[116:117], v[126:127] op_sel_hi:[0,1]
	v_pk_fma_f32 v[126:127], v[62:63], v[118:119], v[154:155]
	v_mov_b32_e32 v118, v171
	v_mov_b32_e32 v119, v121
	v_pk_mul_f32 v[122:123], v[116:117], v[122:123] op_sel_hi:[0,1]
	v_pk_mul_f32 v[118:119], v[116:117], v[118:119] op_sel_hi:[0,1]
	v_pk_mul_f32 v[122:123], v[6:7], v[122:123]
	v_pk_mul_f32 v[124:125], v[0:1], v[124:125]
	v_pk_mul_f32 v[118:119], v[14:15], v[118:119]
	v_mov_b32_e32 v171, v120
	v_pk_fma_f32 v[122:123], v[58:59], v[122:123], v[150:151]
	v_pk_fma_f32 v[124:125], v[64:65], v[124:125], v[152:153]
	v_mov_b32_e32 v150, v167
	v_mov_b32_e32 v151, v169
	v_pk_fma_f32 v[152:153], v[66:67], v[118:119], v[158:159]
	v_pk_mul_f32 v[118:119], v[116:117], v[170:171] op_sel_hi:[0,1]
	v_mov_b32_e32 v167, v168
	v_pk_mul_f32 v[172:173], v[116:117], v[172:173] op_sel_hi:[0,1]
	v_pk_mul_f32 v[150:151], v[116:117], v[150:151] op_sel_hi:[0,1]
	v_pk_mul_f32 v[116:117], v[116:117], v[166:167] op_sel_hi:[0,1]
	v_pk_mul_f32 v[118:119], v[10:11], v[118:119]
	v_pk_mul_f32 v[172:173], v[4:5], v[172:173]
	v_pk_mul_f32 v[116:117], v[8:9], v[116:117]
	v_pk_fma_f32 v[120:121], v[70:71], v[118:119], v[162:163]
	v_cvt_pk_bf16_f32 v118, v124, v125
	v_cvt_pk_bf16_f32 v119, v126, v127
	v_pk_fma_f32 v[130:131], v[60:61], v[172:173], v[130:131]
	v_pk_mul_f32 v[150:151], v[12:13], v[150:151]
	v_pk_fma_f32 v[154:155], v[72:73], v[116:117], v[160:161]
	v_cvt_pk_bf16_f32 v116, v130, v131
	v_cvt_pk_bf16_f32 v117, v122, v123
	global_store_dwordx4 v[128:129], v[116:119], off nt
	v_pk_fma_f32 v[150:151], v[68:69], v[150:151], v[156:157]
	s_addc_u32 s3, s3, 0
	v_cvt_pk_bf16_f32 v118, v154, v155
	v_cvt_pk_bf16_f32 v119, v120, v121
	v_cvt_pk_bf16_f32 v116, v150, v151
	v_cvt_pk_bf16_f32 v117, v152, v153
	global_store_dwordx4 v[128:129], v[116:119], off offset:1024 nt
	v_mov_b32_e32 v128, v155
	v_mov_b32_e32 v129, v151
	v_mov_b32_e32 v118, v131
	v_mov_b32_e32 v119, v125
	v_mov_b32_e32 v116, v130
	v_mov_b32_e32 v117, v124
	v_pk_mul_f32 v[118:119], v[118:119], v[118:119]
	v_pk_mul_f32 v[128:129], v[128:129], v[128:129]
	v_pk_fma_f32 v[116:117], v[116:117], v[116:117], v[118:119]
	v_mov_b32_e32 v118, v122
	v_mov_b32_e32 v119, v126
	v_pk_fma_f32 v[116:117], v[118:119], v[118:119], v[116:117]
	v_mov_b32_e32 v118, v123
	v_mov_b32_e32 v119, v127
	v_pk_fma_f32 v[116:117], v[118:119], v[118:119], v[116:117]
	v_mov_b32_e32 v118, v154
	v_mov_b32_e32 v119, v150
	v_pk_fma_f32 v[118:119], v[118:119], v[118:119], v[128:129]
	v_mov_b32_e32 v128, v120
	v_mov_b32_e32 v129, v152
	v_pk_fma_f32 v[118:119], v[128:129], v[128:129], v[118:119]
	v_mov_b32_e32 v128, v121
	v_mov_b32_e32 v129, v153
	v_pk_fma_f32 v[118:119], v[128:129], v[128:129], v[118:119]
	v_add_f32_e32 v116, v116, v117
	v_add_f32_e32 v116, v119, v116
	v_add_f32_e32 v116, v118, v116
	s_cmp_lt_i32 s2, s8
	s_nop 0
	v_add_f32_dpp v116, v116, v116 quad_perm:[1,0,3,2] row_mask:0xf bank_mask:0xf bound_ctrl:1
	s_nop 1
	v_add_f32_dpp v116, v116, v116 quad_perm:[2,3,0,1] row_mask:0xf bank_mask:0xf bound_ctrl:1
	s_nop 1
	v_add_f32_dpp v116, v116, v116 row_half_mirror row_mask:0xf bank_mask:0xf bound_ctrl:1
	s_nop 1
	v_add_f32_dpp v116, v116, v116 row_mirror row_mask:0xf bank_mask:0xf bound_ctrl:1
	s_nop 0
	v_readlane_b32 s6, v116, 16
	v_readlane_b32 s7, v116, 48
	v_readlane_b32 s4, v116, 0
	v_readlane_b32 s5, v116, 32
	v_mov_b32_e32 v116, s6
	v_mov_b32_e32 v117, s7
	v_pk_add_f32 v[116:117], s[4:5], v[116:117]
	s_nop 0
	v_add_f32_e32 v116, v116, v117
	v_fmamk_f32 v116, v116, 0x3a800000, v137
	v_cmp_gt_f32_e32 vcc, s94, v116
	v_mul_f32_e32 v117, 0x4b800000, v116
	s_nop 0
	v_cndmask_b32_e32 v116, v116, v117, vcc
	v_rsq_f32_e32 v116, v116
	s_nop 0
	v_mul_f32_e32 v117, 0x45800000, v116
	v_cndmask_b32_e32 v116, v116, v117, vcc
	v_pk_mul_f32 v[118:119], v[122:123], v[116:117] op_sel_hi:[1,0]
	v_pk_mul_f32 v[122:123], v[130:131], v[116:117] op_sel_hi:[1,0]
	v_pk_mul_f32 v[118:119], v[30:31], v[118:119]
	v_pk_mul_f32 v[126:127], v[126:127], v[116:117] op_sel_hi:[1,0]
	v_pk_mul_f32 v[124:125], v[124:125], v[116:117] op_sel_hi:[1,0]
	v_pk_mul_f32 v[128:129], v[152:153], v[116:117] op_sel_hi:[1,0]
	v_pk_mul_f32 v[130:131], v[150:151], v[116:117] op_sel_hi:[1,0]
	v_pk_mul_f32 v[120:121], v[120:121], v[116:117] op_sel_hi:[1,0]
	v_pk_mul_f32 v[116:117], v[154:155], v[116:117] op_sel_hi:[1,0]
	v_pk_fma_f32 v[118:119], v[74:75], v[118:119], v[22:23]
	v_pk_mul_f32 v[124:125], v[24:25], v[124:125]
	v_pk_mul_f32 v[126:127], v[26:27], v[126:127]
	v_pk_mul_f32 v[116:117], v[40:41], v[116:117]
	v_pk_mul_f32 v[122:123], v[28:29], v[122:123]
	v_pk_fma_f32 v[126:127], v[78:79], v[126:127], v[18:19]
	v_pk_fma_f32 v[124:125], v[80:81], v[124:125], v[16:17]
	v_pk_mul_f32 v[120:121], v[42:43], v[120:121]
	v_pk_fma_f32 v[150:151], v[88:89], v[116:117], v[32:33]
	v_cvt_pk_bf16_f32 v117, v118, v119
	v_cvt_pk_bf16_f32 v118, v124, v125
	v_cvt_pk_bf16_f32 v119, v126, v127
	v_pk_fma_f32 v[122:123], v[76:77], v[122:123], v[20:21]
	v_pk_mul_f32 v[130:131], v[44:45], v[130:131]
	v_pk_mul_f32 v[128:129], v[46:47], v[128:129]
	v_pk_fma_f32 v[120:121], v[86:87], v[120:121], v[34:35]
	v_cvt_pk_bf16_f32 v116, v122, v123
	global_store_dwordx4 v[94:95], v[116:119], off nt
	v_pk_fma_f32 v[128:129], v[82:83], v[128:129], v[38:39]
	v_pk_fma_f32 v[130:131], v[84:85], v[130:131], v[36:37]
	v_cvt_pk_bf16_f32 v118, v150, v151
	v_cvt_pk_bf16_f32 v119, v120, v121
	v_cvt_pk_bf16_f32 v117, v128, v129
	s_waitcnt vmcnt(4)
	v_lshlrev_b32_e32 v120, 16, v53
	v_cvt_pk_bf16_f32 v116, v130, v131
	global_store_dwordx4 v[94:95], v[116:119], off offset:1024 nt
	s_waitcnt vmcnt(4)
	v_and_b32_e32 v125, 0xffff0000, v48
	v_and_b32_e32 v124, 0xffff0000, v50
	v_and_b32_e32 v119, 0xffff0000, v54
	v_and_b32_e32 v118, 0xffff0000, v52
	v_lshlrev_b32_e32 v117, 16, v54
	v_lshlrev_b32_e32 v116, 16, v52
	v_and_b32_e32 v54, 0xffff0000, v53
	v_pk_mul_f32 v[52:53], v[118:119], v[118:119]
	v_lshlrev_b32_e32 v121, 16, v55
	v_pk_fma_f32 v[52:53], v[116:117], v[116:117], v[52:53]
	v_lshlrev_b32_e32 v123, 16, v48
	v_lshlrev_b32_e32 v122, 16, v50
	v_lshlrev_b32_e32 v126, 16, v51
	v_and_b32_e32 v48, 0xffff0000, v51
	v_pk_mul_f32 v[50:51], v[124:125], v[124:125]
	v_and_b32_e32 v55, 0xffff0000, v55
	v_pk_fma_f32 v[52:53], v[120:121], v[120:121], v[52:53]
	v_lshlrev_b32_e32 v127, 16, v49
	v_pk_fma_f32 v[50:51], v[122:123], v[122:123], v[50:51]
	v_pk_fma_f32 v[52:53], v[54:55], v[54:55], v[52:53]
	v_and_b32_e32 v49, 0xffff0000, v49
	v_pk_fma_f32 v[50:51], v[126:127], v[126:127], v[50:51]
	v_add_f32_e32 v52, v52, v53
	v_pk_fma_f32 v[50:51], v[48:49], v[48:49], v[50:51]
	v_mov_b32_e32 v53, v54
	v_add_f32_e32 v51, v52, v51
	v_add_f32_e32 v50, v50, v51
	v_mov_b32_e32 v52, v120
	v_mov_b32_e32 v129, v118
	v_add_f32_dpp v50, v50, v50 quad_perm:[1,0,3,2] row_mask:0xf bank_mask:0xf bound_ctrl:1
	v_mov_b32_e32 v54, v121
	v_mov_b32_e32 v118, v117
	v_add_f32_dpp v50, v50, v50 quad_perm:[2,3,0,1] row_mask:0xf bank_mask:0xf bound_ctrl:1
	v_mov_b32_e32 v128, v116
	v_lshl_add_u64 v[94:95], v[94:95], 0, s[30:31]
	v_add_f32_dpp v50, v50, v50 row_half_mirror row_mask:0xf bank_mask:0xf bound_ctrl:1
	s_nop 1
	v_add_f32_dpp v50, v50, v50 row_mirror row_mask:0xf bank_mask:0xf bound_ctrl:1
	s_nop 0
	v_readlane_b32 s6, v50, 16
	v_readlane_b32 s7, v50, 48
	v_readlane_b32 s4, v50, 0
	v_readlane_b32 s5, v50, 32
	v_mov_b32_e32 v50, s6
	v_mov_b32_e32 v51, s7
	v_pk_add_f32 v[50:51], s[4:5], v[50:51]
	s_nop 0
	v_add_f32_e32 v50, v50, v51
	v_fmamk_f32 v50, v50, 0x3a800000, v137
	v_cmp_gt_f32_e32 vcc, s94, v50
	v_mul_f32_e32 v51, 0x4b800000, v50
	s_nop 0
	v_cndmask_b32_e32 v50, v50, v51, vcc
	v_rsq_f32_e32 v50, v50
	s_nop 0
	v_mul_f32_e32 v51, 0x45800000, v50
	v_cndmask_b32_e32 v50, v50, v51, vcc
	v_pk_mul_f32 v[52:53], v[50:51], v[52:53] op_sel_hi:[0,1]
	v_pk_mul_f32 v[52:53], v[6:7], v[52:53]
	v_pk_mul_f32 v[54:55], v[50:51], v[54:55] op_sel_hi:[0,1]
	v_pk_fma_f32 v[52:53], v[58:59], v[52:53], v[114:115]
	v_pk_mul_f32 v[114:115], v[50:51], v[118:119] op_sel_hi:[0,1]
	v_pk_mul_f32 v[114:115], v[0:1], v[114:115]
	v_pk_mul_f32 v[54:55], v[2:3], v[54:55]
	v_pk_fma_f32 v[108:109], v[64:65], v[114:115], v[108:109]
	v_pk_fma_f32 v[54:55], v[62:63], v[54:55], v[110:111]
	v_mov_b32_e32 v110, v127
	v_mov_b32_e32 v111, v49
	v_mov_b32_e32 v114, v123
	v_mov_b32_e32 v115, v125
	v_mov_b32_e32 v127, v48
	v_mov_b32_e32 v123, v124
	v_pk_mul_f32 v[128:129], v[50:51], v[128:129] op_sel_hi:[0,1]
	v_pk_mul_f32 v[110:111], v[50:51], v[110:111] op_sel_hi:[0,1]
	v_pk_mul_f32 v[114:115], v[50:51], v[114:115] op_sel_hi:[0,1]
	v_pk_mul_f32 v[48:49], v[50:51], v[126:127] op_sel_hi:[0,1]
	v_pk_mul_f32 v[50:51], v[50:51], v[122:123] op_sel_hi:[0,1]
	v_pk_mul_f32 v[50:51], v[8:9], v[50:51]
	v_pk_mul_f32 v[128:129], v[4:5], v[128:129]
	v_pk_mul_f32 v[48:49], v[10:11], v[48:49]
	v_pk_fma_f32 v[100:101], v[72:73], v[50:51], v[100:101]
	v_cvt_pk_bf16_f32 v50, v108, v109
	v_cvt_pk_bf16_f32 v51, v54, v55
	v_pk_fma_f32 v[112:113], v[60:61], v[128:129], v[112:113]
	v_pk_mul_f32 v[114:115], v[12:13], v[114:115]
	v_pk_mul_f32 v[110:111], v[14:15], v[110:111]
	v_pk_fma_f32 v[102:103], v[70:71], v[48:49], v[102:103]
	v_cvt_pk_bf16_f32 v48, v112, v113
	v_cvt_pk_bf16_f32 v49, v52, v53
	global_store_dwordx4 v[98:99], v[48:51], off nt
	v_pk_fma_f32 v[106:107], v[66:67], v[110:111], v[106:107]
	v_pk_fma_f32 v[104:105], v[68:69], v[114:115], v[104:105]
	v_cvt_pk_bf16_f32 v50, v100, v101
	v_cvt_pk_bf16_f32 v51, v102, v103
	v_cvt_pk_bf16_f32 v49, v106, v107
	s_nop 0
	v_cvt_pk_bf16_f32 v48, v104, v105
	global_store_dwordx4 v[98:99], v[48:51], off offset:1024 nt
	v_mov_b32_e32 v98, v101
	v_mov_b32_e32 v99, v105
	v_mov_b32_e32 v50, v113
	v_mov_b32_e32 v51, v109
	v_mov_b32_e32 v48, v112
	v_mov_b32_e32 v49, v108
	v_pk_mul_f32 v[50:51], v[50:51], v[50:51]
	v_pk_mul_f32 v[98:99], v[98:99], v[98:99]
	v_pk_fma_f32 v[48:49], v[48:49], v[48:49], v[50:51]
	v_mov_b32_e32 v50, v52
	v_mov_b32_e32 v51, v54
	v_pk_fma_f32 v[48:49], v[50:51], v[50:51], v[48:49]
	v_mov_b32_e32 v50, v53
	v_mov_b32_e32 v51, v55
	v_pk_fma_f32 v[48:49], v[50:51], v[50:51], v[48:49]
	v_mov_b32_e32 v50, v100
	v_mov_b32_e32 v51, v104
	v_pk_fma_f32 v[50:51], v[50:51], v[50:51], v[98:99]
	v_mov_b32_e32 v98, v102
	v_mov_b32_e32 v99, v106
	v_pk_fma_f32 v[50:51], v[98:99], v[98:99], v[50:51]
	v_mov_b32_e32 v98, v103
	v_mov_b32_e32 v99, v107
	v_pk_fma_f32 v[50:51], v[98:99], v[98:99], v[50:51]
	v_add_f32_e32 v48, v48, v49
	v_add_f32_e32 v48, v51, v48
	v_add_f32_e32 v48, v50, v48
	s_nop 1
	v_add_f32_dpp v48, v48, v48 quad_perm:[1,0,3,2] row_mask:0xf bank_mask:0xf bound_ctrl:1
	s_nop 1
	v_add_f32_dpp v48, v48, v48 quad_perm:[2,3,0,1] row_mask:0xf bank_mask:0xf bound_ctrl:1
	s_nop 1
	v_add_f32_dpp v48, v48, v48 row_half_mirror row_mask:0xf bank_mask:0xf bound_ctrl:1
	s_nop 1
	v_add_f32_dpp v48, v48, v48 row_mirror row_mask:0xf bank_mask:0xf bound_ctrl:1
	s_nop 0
	v_readlane_b32 s6, v48, 16
	v_readlane_b32 s7, v48, 48
	v_readlane_b32 s4, v48, 0
	v_readlane_b32 s5, v48, 32
	v_mov_b32_e32 v48, s6
	v_mov_b32_e32 v49, s7
	v_pk_add_f32 v[48:49], s[4:5], v[48:49]
	s_nop 0
	v_add_f32_e32 v48, v48, v49
	v_fmamk_f32 v48, v48, 0x3a800000, v137
	v_cmp_gt_f32_e32 vcc, s94, v48
	v_mul_f32_e32 v49, 0x4b800000, v48
	s_nop 0
	v_cndmask_b32_e32 v48, v48, v49, vcc
	v_rsq_f32_e32 v48, v48
	s_nop 0
	v_mul_f32_e32 v49, 0x45800000, v48
	v_cndmask_b32_e32 v48, v48, v49, vcc
	v_pk_mul_f32 v[50:51], v[52:53], v[48:49] op_sel_hi:[1,0]
	v_pk_mul_f32 v[52:53], v[112:113], v[48:49] op_sel_hi:[1,0]
	v_pk_mul_f32 v[50:51], v[30:31], v[50:51]
	v_pk_mul_f32 v[54:55], v[54:55], v[48:49] op_sel_hi:[1,0]
	v_pk_mul_f32 v[98:99], v[108:109], v[48:49] op_sel_hi:[1,0]
	v_pk_mul_f32 v[106:107], v[106:107], v[48:49] op_sel_hi:[1,0]
	v_pk_mul_f32 v[104:105], v[104:105], v[48:49] op_sel_hi:[1,0]
	v_pk_mul_f32 v[102:103], v[102:103], v[48:49] op_sel_hi:[1,0]
	v_pk_mul_f32 v[48:49], v[100:101], v[48:49] op_sel_hi:[1,0]
	v_pk_mul_f32 v[52:53], v[28:29], v[52:53]
	v_pk_fma_f32 v[50:51], v[74:75], v[50:51], v[22:23]
	v_pk_mul_f32 v[98:99], v[24:25], v[98:99]
	v_pk_mul_f32 v[54:55], v[26:27], v[54:55]
	v_pk_mul_f32 v[48:49], v[40:41], v[48:49]
	v_pk_fma_f32 v[52:53], v[76:77], v[52:53], v[20:21]
	v_pk_fma_f32 v[54:55], v[78:79], v[54:55], v[18:19]
	v_pk_fma_f32 v[98:99], v[80:81], v[98:99], v[16:17]
	v_pk_mul_f32 v[104:105], v[44:45], v[104:105]
	v_pk_mul_f32 v[106:107], v[46:47], v[106:107]
	v_pk_mul_f32 v[100:101], v[42:43], v[102:103]
	v_pk_fma_f32 v[102:103], v[88:89], v[48:49], v[32:33]
	v_cvt_pk_bf16_f32 v48, v52, v53
	v_cvt_pk_bf16_f32 v49, v50, v51
	v_cvt_pk_bf16_f32 v50, v98, v99
	v_cvt_pk_bf16_f32 v51, v54, v55
	v_pk_fma_f32 v[106:107], v[82:83], v[106:107], v[38:39]
	v_pk_fma_f32 v[104:105], v[84:85], v[104:105], v[36:37]
	v_pk_fma_f32 v[100:101], v[86:87], v[100:101], v[34:35]
	global_store_dwordx4 v[96:97], v[48:51], off nt
	s_nop 1
	v_cvt_pk_bf16_f32 v48, v104, v105
	v_cvt_pk_bf16_f32 v49, v106, v107
	v_cvt_pk_bf16_f32 v50, v102, v103
	v_cvt_pk_bf16_f32 v51, v100, v101
	global_store_dwordx4 v[96:97], v[48:51], off offset:1024 nt
	s_cbranch_scc1 .LBB0_1086
